# attention exp blocks (attnA, B2) and B1 score loop: packed v_pk_add_f32 / v_pk_fma_f32 split into scalar v_add_f32 / v_fmac_f32 (same association, bit-identical)
# speedup vs baseline: 1.0043x; 1.0043x over previous
; #define LAS __attribute__((address_space(3)))
; __device__ __forceinline__ unsigned cvtpk(float lo, float hi) { f32x2_t v = {lo, hi}; bf16x2_t b = __builtin_convertvector(v, bf16x2_t); return __builtin_bit_cast(unsigned, b); }
; __device__ __forceinline__ int pi_row(int i) { return (i & ~12) | ((i & 4) << 1) | ((i & 8) >> 1); }
; #define MFMA32(a, b, c) __builtin_amdgcn_mfma_f32_32x32x16_bf16((a), (b), (c), 0, 0, 0)
; template <bool INIT = true> __device__ __forceinline__ void qk_lds(f32x16& p0, f32x16& p1, const LAS unsigned char* buf, const bf16x8 (&qr)[4], int r32, int hi) {
;     const LAS unsigned char* kp = buf + pi_row(r32) * TP + hi * 16;
;     if (INIT) { p0 = (f32x16){}; p1 = (f32x16){}; }
;     bf16x8 kf[8];
; #pragma unroll
;     for (int d0 = 0; d0 < 4; ++d0) { kf[2 * d0] = *(const LAS bf16x8*)(kp + d0 * 32); kf[2 * d0 + 1] = *(const LAS bf16x8*)(kp + 32 * TP + d0 * 32); }
;     __builtin_amdgcn_s_setprio(1);
; #pragma unroll
;     for (int d0 = 0; d0 < 4; ++d0) { p0 = MFMA32(kf[2 * d0], qr[d0], p0); p1 = MFMA32(kf[2 * d0 + 1], qr[d0], p1); }
;     __builtin_amdgcn_s_setprio(0);
; }
; __device__ __forceinline__ void pv_lds(f32x16& o0, f32x16& o1, const LAS unsigned char* buf, const f32x16& p0, const f32x16& p1, int r32, int hi) {
;     const LAS unsigned char* vp = buf + TILE_B + r32 * TP + hi * 16;
;     bf16x8 pf[4], vf[8];
; #pragma unroll
;     for (int half = 0; half < 2; ++half)
; #pragma unroll
;         for (int s = 0; s < 2; ++s) {
;             const f32x16& p = half ? p1 : p0;
;             u32x4 w; w.x = cvtpk(p[8 * s + 0], p[8 * s + 1]); w.y = cvtpk(p[8 * s + 2], p[8 * s + 3]); w.z = cvtpk(p[8 * s + 4], p[8 * s + 5]); w.w = cvtpk(p[8 * s + 6], p[8 * s + 7]);
;             pf[half * 2 + s] = __builtin_bit_cast(bf16x8, w);
;             vf[(half * 2 + s) * 2] = *(const LAS bf16x8*)(vp + half * 64 + s * 32); vf[(half * 2 + s) * 2 + 1] = *(const LAS bf16x8*)(vp + 32 * TP + half * 64 + s * 32);
;         }
;     __builtin_amdgcn_s_setprio(1);
; #pragma unroll
;     for (int k = 0; k < 4; ++k) { o0 = MFMA32(vf[2 * k], pf[k], o0); o1 = MFMA32(vf[2 * k + 1], pf[k], o1); }
;     __builtin_amdgcn_s_setprio(0);
; }
.LBB0_501:
	v_add3_u32 v0, s28, v137, v138
	ds_read_b128 v[2:5], v0
	ds_read_b128 v[6:9], v0 offset:32
	ds_read_b128 v[10:13], v0 offset:4608
	ds_read_b128 v[204:207], v0 offset:4640
	ds_read_b128 v[208:211], v0 offset:64
	ds_read_b128 v[216:219], v0 offset:96
	ds_read_b128 v[220:223], v0 offset:4672
	ds_read_b128 v[224:227], v0 offset:4704
	s_setprio 1
	s_waitcnt lgkmcnt(7)
	v_mfma_f32_32x32x16_bf16 v[48:63], v[2:5], v[84:87], v[48:63]
	s_waitcnt lgkmcnt(5)
	v_mfma_f32_32x32x16_bf16 v[64:79], v[10:13], v[84:87], v[64:79]
	v_mfma_f32_32x32x16_bf16 v[48:63], v[6:9], v[88:91], v[48:63]
	s_waitcnt lgkmcnt(4)
	v_mfma_f32_32x32x16_bf16 v[64:79], v[204:207], v[88:91], v[64:79]
	s_waitcnt lgkmcnt(3)
	v_mfma_f32_32x32x16_bf16 v[48:63], v[208:211], v[96:99], v[48:63]
	s_waitcnt lgkmcnt(1)
	v_mfma_f32_32x32x16_bf16 v[64:79], v[220:223], v[96:99], v[64:79]
	v_mfma_f32_32x32x16_bf16 v[48:63], v[216:219], v[100:103], v[48:63]
	s_waitcnt lgkmcnt(0)
	v_mfma_f32_32x32x16_bf16 v[64:79], v[224:227], v[100:103], v[64:79]
	s_setprio 0
	s_nop 8
	v_exp_f32_e32 v206, v48
	s_nop 0
	v_exp_f32_e32 v207, v64
	v_exp_f32_e32 v2, v49
	v_exp_f32_e32 v0, v65
	v_exp_f32_e32 v208, v66
	v_add_f32_e32 v3, v206, v207
	v_exp_f32_e32 v72, v72
	v_add_f32_e32 v4, v2, v0
	v_add_f32_e32 v5, v3, v1
	v_exp_f32_e32 v3, v50
	v_add_f32_e32 v15, v4, v5
	v_exp_f32_e32 v4, v51
	v_exp_f32_e32 v14, v67
	v_add_f32_e32 v5, v3, v208
	v_cvt_pk_bf16_f32 v2, v206, v2
	v_cvt_pk_bf16_f32 v3, v3, v4
	v_add_f32_e32 v6, v4, v14
	v_add_f32_e32 v7, v5, v15
	v_exp_f32_e32 v5, v52
	v_add_f32_e32 v65, v6, v7
	v_exp_f32_e32 v15, v68
	v_exp_f32_e32 v6, v53
	v_exp_f32_e32 v64, v69
	v_add_f32_e32 v7, v5, v15
	v_cvt_pk_bf16_f32 v4, v5, v6
	v_add_f32_e32 v8, v6, v64
	v_add_f32_e32 v9, v7, v65
	v_exp_f32_e32 v7, v54
	v_add_f32_e32 v67, v8, v9
	v_exp_f32_e32 v65, v70
	v_exp_f32_e32 v8, v55
	v_exp_f32_e32 v66, v71
	v_exp_f32_e32 v54, v56
	v_add_f32_e32 v9, v7, v65
	v_cvt_pk_bf16_f32 v5, v7, v8
	v_add_f32_e32 v10, v8, v66
	v_add_f32_e32 v11, v9, v67
	s_nop 0
	v_add_f32_e32 v203, v10, v11
	v_exp_f32_e32 v10, v57
	v_exp_f32_e32 v202, v73
	v_add_f32_e32 v11, v54, v72
	v_exp_f32_e32 v73, v74
	v_add_f32_e32 v12, v10, v202
	v_add_f32_e32 v13, v11, v203
	s_nop 0
	v_add_f32_e32 v205, v12, v13
	v_exp_f32_e32 v11, v58
	v_exp_f32_e32 v12, v59
	v_exp_f32_e32 v204, v75
	v_exp_f32_e32 v203, v76
	v_add_f32_e32 v13, v11, v73
	v_cvt_pk_bf16_f32 v10, v54, v10
	v_add_f32_e32 v48, v12, v204
	v_add_f32_e32 v49, v13, v205
	v_exp_f32_e32 v13, v60
	v_add_f32_e32 v75, v48, v49
	v_exp_f32_e32 v48, v61
	v_exp_f32_e32 v74, v77
	v_add_f32_e32 v49, v13, v203
	v_add3_u32 v205, s28, v139, v138
	v_cvt_pk_bf16_f32 v11, v11, v12
	v_add_f32_e32 v50, v48, v74
	v_add_f32_e32 v51, v49, v75
	v_exp_f32_e32 v49, v62
	v_add_f32_e32 v77, v50, v51
	v_exp_f32_e32 v75, v78
	v_exp_f32_e32 v50, v63
	v_exp_f32_e32 v76, v79
	v_cvt_pk_bf16_f32 v12, v13, v48
	v_add_f32_e32 v51, v49, v75
	v_cvt_pk_bf16_f32 v13, v49, v50
	v_add_f32_e32 v52, v50, v76
	v_add_f32_e32 v53, v51, v77
	v_cvt_pk_bf16_f32 v60, v207, v0
	v_add_f32_e32 v9, v52, v53
	v_add_f32_e32 v214, v214, v9
	ds_read_b128 v[6:9], v205 offset:13824
	ds_read_b128 v[48:51], v205 offset:9216
	ds_read_b128 v[52:55], v205 offset:9248
	ds_read_b128 v[56:59], v205 offset:13856
	v_cvt_pk_bf16_f32 v62, v15, v64
	v_cvt_pk_bf16_f32 v63, v65, v66
	ds_read_b128 v[64:67], v205 offset:9280
	ds_read_b128 v[68:71], v205 offset:13888
	v_cvt_pk_bf16_f32 v73, v73, v204
	v_cvt_pk_bf16_f32 v75, v75, v76
	ds_read_b128 v[76:79], v205 offset:9312
	ds_read_b128 v[204:207], v205 offset:13920
	v_cvt_pk_bf16_f32 v61, v208, v14
	v_cvt_pk_bf16_f32 v72, v72, v202
	v_cvt_pk_bf16_f32 v74, v203, v74
	s_setprio 1
	s_waitcnt lgkmcnt(6)
	v_mfma_f32_32x32x16_bf16 v[32:47], v[48:51], v[2:5], v[32:47]
	v_mfma_f32_32x32x16_bf16 v[16:31], v[6:9], v[2:5], v[16:31]
	s_waitcnt lgkmcnt(5)
	v_mfma_f32_32x32x16_bf16 v[32:47], v[52:55], v[10:13], v[32:47]
	s_waitcnt lgkmcnt(4)
	v_mfma_f32_32x32x16_bf16 v[16:31], v[56:59], v[10:13], v[16:31]
	s_waitcnt lgkmcnt(3)
	v_mfma_f32_32x32x16_bf16 v[32:47], v[64:67], v[60:63], v[32:47]
	s_waitcnt lgkmcnt(2)
	v_mfma_f32_32x32x16_bf16 v[16:31], v[68:71], v[60:63], v[16:31]
	s_waitcnt lgkmcnt(1)
	v_mfma_f32_32x32x16_bf16 v[32:47], v[76:79], v[72:75], v[32:47]
	s_waitcnt lgkmcnt(0)
	v_mfma_f32_32x32x16_bf16 v[16:31], v[204:207], v[72:75], v[16:31]
	s_setprio 0

.LBB0_512:
	v_add3_u32 v0, s28, v137, v138
	ds_read_b128 v[2:5], v0 offset:18432
	ds_read_b128 v[6:9], v0 offset:18464
	ds_read_b128 v[10:13], v0 offset:23040
	ds_read_b128 v[204:207], v0 offset:23072
	ds_read_b128 v[208:211], v0 offset:18496
	ds_read_b128 v[216:219], v0 offset:18528
	ds_read_b128 v[220:223], v0 offset:23104
	ds_read_b128 v[224:227], v0 offset:23136
	s_setprio 1
	s_waitcnt lgkmcnt(7)
	v_mfma_f32_32x32x16_bf16 v[64:79], v[2:5], v[84:87], v[64:79]
	s_waitcnt lgkmcnt(5)
	v_mfma_f32_32x32x16_bf16 v[48:63], v[10:13], v[84:87], v[48:63]
	v_mfma_f32_32x32x16_bf16 v[64:79], v[6:9], v[88:91], v[64:79]
	s_waitcnt lgkmcnt(4)
	v_mfma_f32_32x32x16_bf16 v[48:63], v[204:207], v[88:91], v[48:63]
	s_waitcnt lgkmcnt(3)
	v_mfma_f32_32x32x16_bf16 v[64:79], v[208:211], v[96:99], v[64:79]
	s_waitcnt lgkmcnt(1)
	v_mfma_f32_32x32x16_bf16 v[48:63], v[220:223], v[96:99], v[48:63]
	v_mfma_f32_32x32x16_bf16 v[64:79], v[216:219], v[100:103], v[64:79]
	s_waitcnt lgkmcnt(0)
	v_mfma_f32_32x32x16_bf16 v[48:63], v[224:227], v[100:103], v[48:63]
	s_setprio 0
	s_nop 8
	v_exp_f32_e32 v206, v64
	s_nop 0
	v_exp_f32_e32 v207, v48
	v_exp_f32_e32 v2, v65
	v_exp_f32_e32 v0, v49
	v_exp_f32_e32 v208, v50
	v_add_f32_e32 v3, v206, v207
	v_add_f32_e32 v4, v2, v0
	v_add_f32_e32 v5, v3, v1
	s_nop 0
	v_add_f32_e32 v15, v4, v5
	v_exp_f32_e32 v3, v66
	v_exp_f32_e32 v4, v67
	v_exp_f32_e32 v14, v51
	v_cvt_pk_bf16_f32 v2, v206, v2
	v_add_f32_e32 v5, v3, v208
	v_cvt_pk_bf16_f32 v3, v3, v4
	v_add_f32_e32 v6, v4, v14
	v_add_f32_e32 v7, v5, v15
	v_exp_f32_e32 v5, v68
	v_add_f32_e32 v65, v6, v7
	v_exp_f32_e32 v15, v52
	v_exp_f32_e32 v6, v69
	v_exp_f32_e32 v64, v53
	v_add_f32_e32 v7, v5, v15
	v_cvt_pk_bf16_f32 v4, v5, v6
	v_add_f32_e32 v8, v6, v64
	v_add_f32_e32 v9, v7, v65
	v_exp_f32_e32 v7, v70
	v_add_f32_e32 v67, v8, v9
	v_exp_f32_e32 v65, v54
	v_exp_f32_e32 v8, v71
	v_exp_f32_e32 v66, v55
	v_exp_f32_e32 v54, v72
	v_add_f32_e32 v9, v7, v65
	v_exp_f32_e32 v72, v56
	v_add_f32_e32 v10, v8, v66
	v_add_f32_e32 v11, v9, v67
	v_cvt_pk_bf16_f32 v5, v7, v8
	v_add_f32_e32 v203, v10, v11
	v_exp_f32_e32 v10, v73
	v_exp_f32_e32 v202, v57
	v_add_f32_e32 v11, v54, v72
	v_exp_f32_e32 v73, v58
	v_add_f32_e32 v12, v10, v202
	v_add_f32_e32 v13, v11, v203
	s_nop 0
	v_add_f32_e32 v205, v12, v13
	v_exp_f32_e32 v11, v74
	v_exp_f32_e32 v12, v75
	v_exp_f32_e32 v204, v59
	v_exp_f32_e32 v203, v60
	v_add_f32_e32 v13, v11, v73
	v_cvt_pk_bf16_f32 v10, v54, v10
	v_add_f32_e32 v48, v12, v204
	v_add_f32_e32 v49, v13, v205
	v_exp_f32_e32 v13, v76
	v_add_f32_e32 v75, v48, v49
	v_exp_f32_e32 v48, v77
	v_exp_f32_e32 v74, v61
	v_add_f32_e32 v49, v13, v203
	v_add3_u32 v205, s28, v139, v138
	v_cvt_pk_bf16_f32 v11, v11, v12
	v_add_f32_e32 v50, v48, v74
	v_add_f32_e32 v51, v49, v75
	v_exp_f32_e32 v49, v78
	v_add_f32_e32 v77, v50, v51
	v_exp_f32_e32 v75, v62
	v_exp_f32_e32 v50, v79
	v_exp_f32_e32 v76, v63
	v_cvt_pk_bf16_f32 v12, v13, v48
	v_add_f32_e32 v51, v49, v75
	v_cvt_pk_bf16_f32 v13, v49, v50
	v_add_f32_e32 v52, v50, v76
	v_add_f32_e32 v53, v51, v77
	v_cvt_pk_bf16_f32 v60, v207, v0
	v_add_f32_e32 v9, v52, v53
	v_add_f32_e32 v214, v214, v9
	ds_read_b128 v[6:9], v205 offset:32256
	ds_read_b128 v[48:51], v205 offset:27648
	ds_read_b128 v[52:55], v205 offset:27680
	ds_read_b128 v[56:59], v205 offset:32288
	v_cvt_pk_bf16_f32 v62, v15, v64
	v_cvt_pk_bf16_f32 v63, v65, v66
	ds_read_b128 v[64:67], v205 offset:27712
	ds_read_b128 v[68:71], v205 offset:32320
	v_cvt_pk_bf16_f32 v73, v73, v204
	v_cvt_pk_bf16_f32 v75, v75, v76
	ds_read_b128 v[76:79], v205 offset:27744
	ds_read_b128 v[204:207], v205 offset:32352
	v_cvt_pk_bf16_f32 v61, v208, v14
	v_cvt_pk_bf16_f32 v72, v72, v202
	v_cvt_pk_bf16_f32 v74, v203, v74
	s_andn2_b64 vcc, exec, s[12:13]
	s_cbranch_vccnz .La_pv_nowrite
	s_andn2_b32 s14, 1, s9
	s_mul_i32 s14, s14, 0x9000
	v_add_u32_e32 v0, s14, v113
	s_waitcnt vmcnt(3)
	ds_write_b128 v0, v[80:83]
	s_waitcnt vmcnt(1)
	ds_write_b128 v0, v[92:95] offset:9216
	ds_write_b128 v0, v[104:107] offset:18432
	s_waitcnt vmcnt(0)
	ds_write_b128 v0, v[108:111] offset:27648
	s_setprio 1
	s_waitcnt lgkmcnt(10)
	v_mfma_f32_32x32x16_bf16 v[32:47], v[48:51], v[2:5], v[32:47]
	v_mfma_f32_32x32x16_bf16 v[16:31], v[6:9], v[2:5], v[16:31]
	s_waitcnt lgkmcnt(9)
	v_mfma_f32_32x32x16_bf16 v[32:47], v[52:55], v[10:13], v[32:47]
	s_waitcnt lgkmcnt(8)
	v_mfma_f32_32x32x16_bf16 v[16:31], v[56:59], v[10:13], v[16:31]
	s_waitcnt lgkmcnt(7)
	v_mfma_f32_32x32x16_bf16 v[32:47], v[64:67], v[60:63], v[32:47]
	s_waitcnt lgkmcnt(6)
	v_mfma_f32_32x32x16_bf16 v[16:31], v[68:71], v[60:63], v[16:31]
	s_waitcnt lgkmcnt(5)
	v_mfma_f32_32x32x16_bf16 v[32:47], v[76:79], v[72:75], v[32:47]
	s_waitcnt lgkmcnt(4)
	v_mfma_f32_32x32x16_bf16 v[16:31], v[204:207], v[72:75], v[16:31]
	s_setprio 0
	s_branch .LBB0_488

; #define LAS __attribute__((address_space(3)))
; __device__ __forceinline__ int pi_row(int i) { return (i & ~12) | ((i & 4) << 1) | ((i & 8) >> 1); }
; #define MFMA32(a, b, c) __builtin_amdgcn_mfma_f32_32x32x16_bf16((a), (b), (c), 0, 0, 0)
; __device__ __forceinline__ void b1_phase(const bf16* QI, const bf16* KI, const float* WI, float* SCRb  , unsigned long long* MASK,
;                                          LAS unsigned char* lds, int vcu, int G, int tid) {
;     ...
;         for (int kt = wid; kt < ntile; kt += NWAVES) {
;             const size_t key0 = (size_t)b * SEQ + (size_t)kt * 64;
;             const bf16* kp = KI + (key0 + pi_row(r32)) * 64 + hi * 8;
;             bf16x8 kf0[4], kf1[4];
; #pragma unroll
;             for (int d0 = 0; d0 < 4; ++d0) { kf0[d0] = *(const bf16x8*)(kp + d0 * 16); kf1[d0] = *(const bf16x8*)(kp + 32 * 64 + d0 * 16); }
;             f32x16 s0 = (f32x16){}, s1 = (f32x16){};
;             int qoff = r32 * QI_PITCH + hi * 8; asm volatile("" : "+v"(qoff));
; #pragma unroll 1
;             for (int hh = 0; hh < 8; ++hh) {
;                 f32x16 a0 = (f32x16){}, a1 = (f32x16){};
;                 const float wh = wl[r32 * 8 + hh];
; #pragma unroll
;                 for (int d0 = 0; d0 < 4; ++d0) { const bf16x8 qf = *(const LAS bf16x8*)(qs + qoff + hh * 64 + d0 * 16); a0 = MFMA32(kf0[d0], qf, a0); a1 = MFMA32(kf1[d0], qf, a1); }
; #pragma unroll
;                 for (int r = 0; r < 16; ++r) { s0[r] = __builtin_fmaf(wh, __builtin_fmaxf(a0[r], 0.f), s0[r]); s1[r] = __builtin_fmaf(wh, __builtin_fmaxf(a1[r], 0.f), s1[r]); }
;             }
;             float* sp = SCRb + (size_t)r32 * 4096 + kt * 64 + 8 * hi;
; #pragma unroll
;             for (int half = 0; half < 2; ++half)
; #pragma unroll
;                 for (int s = 0; s < 2; ++s) { const f32x16& p = half ? s1 : s0;
;                     *(f32x4*)(sp + 32 * half + 16 * s) = (f32x4){p[8 * s], p[8 * s + 1], p[8 * s + 2], p[8 * s + 3]};
;                     *(f32x4*)(sp + 32 * half + 16 * s + 4) = (f32x4){p[8 * s + 4], p[8 * s + 5], p[8 * s + 6], p[8 * s + 7]}; }
.LBB0_531:
	ds_read_b128 v[18:21], v0
	ds_read_b128 v[118:121], v0 offset:32
	v_add_u32_e32 v117, s1, v116
	ds_read_b32 v122, v117
	s_add_i32 s1, s1, 4
	s_waitcnt vmcnt(7) lgkmcnt(2)
	v_mfma_f32_32x32x16_bf16 v[2:17], v[50:53], v[18:21], 0
	s_cmp_eq_u32 s1, 32
	s_waitcnt vmcnt(5)
	v_mfma_f32_32x32x16_bf16 v[18:33], v[58:61], v[18:21], 0
	s_waitcnt lgkmcnt(1)
	v_mfma_f32_32x32x16_bf16 v[2:17], v[54:57], v[118:121], v[2:17]
	s_waitcnt vmcnt(4)
	v_mfma_f32_32x32x16_bf16 v[18:33], v[62:65], v[118:121], v[18:33]
	ds_read_b128 v[118:121], v0 offset:64
	s_waitcnt vmcnt(3) lgkmcnt(0)
	v_mfma_f32_32x32x16_bf16 v[2:17], v[66:69], v[118:121], v[2:17]
	s_waitcnt vmcnt(1)
	v_mfma_f32_32x32x16_bf16 v[18:33], v[78:81], v[118:121], v[18:33]
	ds_read_b128 v[118:121], v0 offset:96
	v_add_u32_e32 v0, 0x80, v0
	s_waitcnt lgkmcnt(0)
	v_mfma_f32_32x32x16_bf16 v[2:17], v[70:73], v[118:121], v[2:17]
	s_waitcnt vmcnt(0)
	v_mfma_f32_32x32x16_bf16 v[18:33], v[82:85], v[118:121], v[18:33]
	s_nop 9
	v_max_f32_e32 v117, v4, v4
	v_max_f32_e32 v118, v5, v5
	v_max_f32_e32 v119, v6, v6
	v_max_f32_e32 v120, v7, v7
	v_max_f32_e32 v121, v8, v8
	v_max_f32_e32 v123, v9, v9
	v_max_f32_e32 v124, v10, v10
	v_max_f32_e32 v125, v11, v11
	v_max_f32_e32 v126, v12, v12
	v_max_f32_e32 v127, v13, v13
	v_max_f32_e32 v128, v14, v14
	v_max_f32_e32 v129, v15, v15
	v_max_f32_e32 v130, v16, v16
	v_max_f32_e32 v131, v17, v17
	v_max_f32_e32 v2, 0, v2
	v_max_f32_e32 v4, 0, v18
	v_max_f32_e32 v3, 0, v3
	v_max_f32_e32 v5, 0, v19
	v_max_f32_e32 v6, 0, v117
	v_max_f32_e32 v8, 0, v20
	v_max_f32_e32 v7, 0, v118
	v_max_f32_e32 v9, 0, v21
	v_max_f32_e32 v10, 0, v119
	v_max_f32_e32 v12, 0, v22
	v_max_f32_e32 v11, 0, v120
	v_max_f32_e32 v13, 0, v23
	v_max_f32_e32 v14, 0, v121
	v_max_f32_e32 v16, 0, v24
	v_max_f32_e32 v15, 0, v123
	v_max_f32_e32 v17, 0, v25
	v_max_f32_e32 v18, 0, v124
	v_max_f32_e32 v20, 0, v26
	v_max_f32_e32 v19, 0, v125
	v_max_f32_e32 v21, 0, v27
	v_max_f32_e32 v22, 0, v126
	v_max_f32_e32 v24, 0, v28
	v_max_f32_e32 v23, 0, v127
	v_max_f32_e32 v25, 0, v29
	v_max_f32_e32 v26, 0, v128
	v_max_f32_e32 v28, 0, v30
	v_max_f32_e32 v27, 0, v129
	v_max_f32_e32 v29, 0, v31
	v_max_f32_e32 v30, 0, v130
	v_max_f32_e32 v32, 0, v32
	v_max_f32_e32 v31, 0, v131
	v_max_f32_e32 v33, 0, v33
	v_fmac_f32_e32 v94, v122, v2
	v_fmac_f32_e32 v95, v122, v3
	v_fmac_f32_e32 v46, v122, v4
	v_fmac_f32_e32 v47, v122, v5
	v_fmac_f32_e32 v96, v122, v6
	v_fmac_f32_e32 v97, v122, v7
	v_fmac_f32_e32 v48, v122, v8
	v_fmac_f32_e32 v49, v122, v9
	v_fmac_f32_e32 v90, v122, v10
	v_fmac_f32_e32 v91, v122, v11
	v_fmac_f32_e32 v42, v122, v12
	v_fmac_f32_e32 v43, v122, v13
	v_fmac_f32_e32 v92, v122, v14
	v_fmac_f32_e32 v93, v122, v15
	v_fmac_f32_e32 v44, v122, v16
	v_fmac_f32_e32 v45, v122, v17
	v_fmac_f32_e32 v86, v122, v18
	v_fmac_f32_e32 v87, v122, v19
	v_fmac_f32_e32 v38, v122, v20
	v_fmac_f32_e32 v39, v122, v21
	v_fmac_f32_e32 v88, v122, v22
	v_fmac_f32_e32 v89, v122, v23
	v_fmac_f32_e32 v40, v122, v24
	v_fmac_f32_e32 v41, v122, v25
	v_fmac_f32_e32 v74, v122, v26
	v_fmac_f32_e32 v75, v122, v27
	v_fmac_f32_e32 v34, v122, v28
	v_fmac_f32_e32 v35, v122, v29
	v_fmac_f32_e32 v76, v122, v30
	v_fmac_f32_e32 v77, v122, v31
	v_fmac_f32_e32 v36, v122, v32
	v_fmac_f32_e32 v37, v122, v33
	s_cbranch_scc0 .LBB0_531
	s_lshl_b32 s4, s0, 6
	s_ashr_i32 s5, s4, 31
	s_add_i32 s0, s0, 8
	v_lshl_add_u64 v[2:3], s[4:5], 2, v[106:107]
	s_cmp_gt_i32 s0, s2
	global_store_dwordx4 v[2:3], v[94:97], off
	global_store_dwordx4 v[2:3], v[90:93], off offset:16
	global_store_dwordx4 v[2:3], v[86:89], off offset:64
	global_store_dwordx4 v[2:3], v[74:77], off offset:80
	global_store_dwordx4 v[2:3], v[46:49], off offset:128
	global_store_dwordx4 v[2:3], v[42:45], off offset:144
	global_store_dwordx4 v[2:3], v[38:41], off offset:192
	global_store_dwordx4 v[2:3], v[34:37], off offset:208
	s_cbranch_scc0 .LBB0_530

; #define LAS __attribute__((address_space(3)))
; __device__ __forceinline__ void b_mask_init(f32x16& p0, f32x16& p1, unsigned long long mw, int hi, float ref) {
;     const int n0 = (int)~((unsigned)mw >> (8 * hi)), n1 = (int)~((unsigned)(mw >> 32) >> (8 * hi)); const int nr = __float_as_int(-ref);
; #pragma unroll
;     for (int r = 0; r < 16; ++r) { const int bit = 16 * (r >> 3) + (r & 7);
;         const int e0 = __builtin_amdgcn_sbfe(n0, bit, 1), e1 = __builtin_amdgcn_sbfe(n1, bit, 1);
;         p0[r] = __int_as_float((e0 & (int)0xFF800000) | (~e0 & nr)); p1[r] = __int_as_float((e1 & (int)0xFF800000) | (~e1 & nr)); }
; }
; __device__ __forceinline__ float exp_tile(f32x16& p0, f32x16& p1) {
;     float sacc = 0.f;
; #pragma unroll
;     for (int r = 0; r < 16; ++r) { p0[r] = __builtin_amdgcn_exp2f(p0[r]); p1[r] = __builtin_amdgcn_exp2f(p1[r]);
;     ...
;         p0[r] = __builtin_amdgcn_exp2f(__builtin_amdgcn_logf(p0[r])); p1[r] = __builtin_amdgcn_exp2f(__builtin_amdgcn_logf(p1[r]));
;     ...
;         sacc += p0[r] + p1[r]; }
;     return sacc;
; }
; template <bool FIXED> __device__ __forceinline__ void attnB_blk(const bf16* Q, const bf16* K, const bf16* Vt, bf16* O, const unsigned long long* MASK, float ref, LAS unsigned char* lds, int vcu, int G, int tid) {
;     ...
;             for (int k = 0; k < 2; ++k) {
;                 if (it + k < ntile) {
;                     LAS unsigned char* buf = pb + k * KVBUF_B;
;                     f32x16 p0, p1; b_mask_init(p0, p1, k ? mb : ma, hi, FIXED ? ref : 0.f);
;                     qk_lds<false>(p0, p1, buf, qr, r32, hi);
;                     if (FIXED) l += exp_tile(p0, p1); else softmax_step(p0, p1, m, l, o0, o1);
;                     pv_lds(o0, o1, buf, p0, p1, r32, hi);
.LBB0_778:
	s_bitcmp1_b32 s18, 0
	s_cselect_b32 s22, 0x9000, 0
	s_add_i32 s22, s22, 0
	s_cmp_gt_i32 s21, s17
	v_add3_u32 v7, s22, v135, v157
	v_add3_u32 v6, s22, v158, v157
	s_cbranch_scc1 .LBB0_784
	v_lshrrev_b32_e32 v0, v134, v2
	v_lshrrev_b32_e32 v2, v134, v3
	v_bfe_i32 v17, v0, 23, 1
	v_bfe_i32 v18, v0, 22, 1
	ds_read_b128 v[8:11], v7 offset:4608
	ds_read_b128 v[12:15], v7
	ds_read_b128 v[160:163], v7 offset:32
	ds_read_b128 v[164:167], v7 offset:4640
	ds_read_b128 v[168:171], v7 offset:64
	ds_read_b128 v[172:175], v7 offset:4672
	ds_read_b128 v[176:179], v7 offset:96
	ds_read_b128 v[180:183], v7 offset:4704
	v_bfi_b32 v79, v17, v16, v240
	v_bfe_i32 v19, v0, 21, 1
	v_bfi_b32 v78, v18, v16, v240
	v_bfe_i32 v20, v0, 20, 1
	v_bfi_b32 v77, v19, v16, v240
	v_bfe_i32 v21, v0, 19, 1
	v_bfi_b32 v76, v20, v16, v240
	v_bfe_i32 v22, v0, 18, 1
	v_bfi_b32 v75, v21, v16, v240
	v_bfe_i32 v23, v0, 17, 1
	v_bfi_b32 v74, v22, v16, v240
	v_bfe_i32 v24, v0, 16, 1
	v_bfi_b32 v73, v23, v16, v240
	v_bfe_i32 v17, v0, 7, 1
	v_bfi_b32 v72, v24, v16, v240
	v_bfe_i32 v18, v0, 6, 1
	v_bfi_b32 v71, v17, v16, v240
	v_bfe_i32 v19, v0, 5, 1
	v_bfi_b32 v70, v18, v16, v240
	v_bfe_i32 v20, v0, 4, 1
	v_bfi_b32 v69, v19, v16, v240
	v_bfe_i32 v21, v0, 3, 1
	v_bfi_b32 v68, v20, v16, v240
	v_bfe_i32 v22, v0, 2, 1
	v_bfi_b32 v67, v21, v16, v240
	v_bfe_i32 v23, v0, 1, 1
	v_bfe_i32 v24, v0, 0, 1
	v_bfi_b32 v66, v22, v16, v240
	v_bfi_b32 v65, v23, v16, v240
	v_bfe_i32 v17, v2, 23, 1
	v_bfi_b32 v64, v24, v16, v240
	v_bfe_i32 v18, v2, 22, 1
	v_bfi_b32 v95, v17, v16, v240
	v_bfe_i32 v19, v2, 21, 1
	v_bfi_b32 v94, v18, v16, v240
	v_bfe_i32 v20, v2, 20, 1
	v_bfi_b32 v93, v19, v16, v240
	v_bfe_i32 v21, v2, 19, 1
	v_bfi_b32 v92, v20, v16, v240
	v_bfe_i32 v22, v2, 18, 1
	v_bfi_b32 v91, v21, v16, v240
	v_bfe_i32 v23, v2, 17, 1
	v_bfi_b32 v90, v22, v16, v240
	v_bfe_i32 v24, v2, 16, 1
	v_bfi_b32 v89, v23, v16, v240
	v_bfe_i32 v17, v2, 7, 1
	v_bfi_b32 v88, v24, v16, v240
	v_bfe_i32 v18, v2, 6, 1
	v_bfi_b32 v87, v17, v16, v240
	v_bfe_i32 v19, v2, 5, 1
	v_bfi_b32 v86, v18, v16, v240
	v_bfe_i32 v20, v2, 4, 1
	v_bfi_b32 v85, v19, v16, v240
	v_bfe_i32 v21, v2, 3, 1
	v_bfi_b32 v84, v20, v16, v240
	v_bfe_i32 v22, v2, 2, 1
	v_bfi_b32 v83, v21, v16, v240
	v_bfe_i32 v23, v2, 1, 1
	v_bfi_b32 v82, v22, v16, v240
	v_bfe_i32 v24, v2, 0, 1
	v_bfi_b32 v81, v23, v16, v240
	v_bfi_b32 v80, v24, v16, v240
	s_setprio 1
	s_waitcnt lgkmcnt(6)
	v_mfma_f32_32x32x16_bf16 v[64:79], v[12:15], v[96:99], v[64:79]
	v_mfma_f32_32x32x16_bf16 v[80:95], v[8:11], v[96:99], v[80:95]
	s_waitcnt lgkmcnt(5)
	v_mfma_f32_32x32x16_bf16 v[64:79], v[160:163], v[100:103], v[64:79]
	s_waitcnt lgkmcnt(4)
	v_mfma_f32_32x32x16_bf16 v[80:95], v[164:167], v[100:103], v[80:95]
	s_waitcnt lgkmcnt(3)
	v_mfma_f32_32x32x16_bf16 v[64:79], v[168:171], v[108:111], v[64:79]
	s_waitcnt lgkmcnt(2)
	v_mfma_f32_32x32x16_bf16 v[80:95], v[172:175], v[108:111], v[80:95]
	s_waitcnt lgkmcnt(1)
	v_mfma_f32_32x32x16_bf16 v[64:79], v[176:179], v[112:115], v[64:79]
	s_waitcnt lgkmcnt(0)
	v_mfma_f32_32x32x16_bf16 v[80:95], v[180:183], v[112:115], v[80:95]
	s_setprio 0
	s_nop 8
	v_exp_f32_e32 v147, v64
	s_nop 0
	v_exp_f32_e32 v80, v80
	v_exp_f32_e32 v2, v65
	v_exp_f32_e32 v0, v81
	v_exp_f32_e32 v81, v82
	v_add_f32_e32 v3, v147, v80
	v_exp_f32_e32 v10, v67
	v_add_f32_e32 v8, v2, v0
	v_add_f32_e32 v9, v3, v1
	v_exp_f32_e32 v3, v66
	v_add_f32_e32 v161, v8, v9
	v_exp_f32_e32 v160, v83
	v_exp_f32_e32 v159, v84
	v_add_f32_e32 v11, v3, v81
	v_exp_f32_e32 v12, v69
	v_add_f32_e32 v8, v10, v160
	v_add_f32_e32 v9, v11, v161
	v_exp_f32_e32 v11, v68
	v_add_f32_e32 v83, v8, v9
	v_exp_f32_e32 v82, v85
	v_exp_f32_e32 v14, v71
	v_add_f32_e32 v13, v11, v159
	v_exp_f32_e32 v72, v72
	v_add_f32_e32 v8, v12, v82
	v_add_f32_e32 v9, v13, v83
	v_exp_f32_e32 v13, v70
	v_add_f32_e32 v85, v8, v9
	v_exp_f32_e32 v83, v86
	v_exp_f32_e32 v84, v87
	v_exp_f32_e32 v161, v88
	v_exp_f32_e32 v64, v73
	v_add_f32_e32 v15, v13, v83
	v_add_f32_e32 v8, v14, v84
	v_add_f32_e32 v9, v15, v85
	v_add_f32_e32 v65, v72, v161
	v_add_f32_e32 v163, v8, v9
	v_exp_f32_e32 v162, v89
	v_exp_f32_e32 v66, v75
	v_exp_f32_e32 v68, v77
	v_exp_f32_e32 v70, v79
	v_add_f32_e32 v8, v64, v162
	v_add_f32_e32 v9, v65, v163
	v_exp_f32_e32 v65, v74
	v_add_f32_e32 v165, v8, v9
	v_exp_f32_e32 v163, v90
	v_exp_f32_e32 v164, v91
	v_cvt_pk_bf16_f32 v64, v72, v64
	v_cvt_pk_bf16_f32 v81, v81, v160
	v_add_f32_e32 v67, v65, v163
	v_add_f32_e32 v8, v66, v164
	v_add_f32_e32 v9, v67, v165
	v_exp_f32_e32 v67, v76
	v_add_f32_e32 v167, v8, v9
	v_exp_f32_e32 v165, v92
	v_exp_f32_e32 v166, v93
	v_cvt_pk_bf16_f32 v65, v65, v66
	v_cvt_pk_bf16_f32 v66, v67, v68
	v_add_f32_e32 v69, v67, v165
	v_add_f32_e32 v8, v68, v166
	v_add_f32_e32 v9, v69, v167
	v_exp_f32_e32 v69, v78
	v_add_f32_e32 v169, v8, v9
	v_exp_f32_e32 v167, v94
	v_exp_f32_e32 v168, v95
	v_cvt_pk_bf16_f32 v67, v69, v70
	v_cvt_pk_bf16_f32 v83, v83, v84
	v_add_f32_e32 v71, v69, v167
	v_add_f32_e32 v8, v70, v168
	v_add_f32_e32 v9, v71, v169
	v_cvt_pk_bf16_f32 v92, v161, v162
	v_add_f32_e32 v8, v8, v9
	v_cvt_pk_bf16_f32 v9, v3, v10
	v_cvt_pk_bf16_f32 v10, v11, v12
	v_cvt_pk_bf16_f32 v11, v13, v14
	ds_read_b128 v[12:15], v6 offset:13824
	ds_read_b128 v[68:71], v6 offset:9216
	ds_read_b128 v[72:75], v6 offset:9248
	ds_read_b128 v[76:79], v6 offset:13856
	ds_read_b128 v[84:87], v6 offset:9280
	ds_read_b128 v[88:91], v6 offset:13888
	v_cvt_pk_bf16_f32 v93, v163, v164
	v_cvt_pk_bf16_f32 v94, v165, v166
	v_cvt_pk_bf16_f32 v95, v167, v168
	ds_read_b128 v[160:163], v6 offset:9312
	ds_read_b128 v[164:167], v6 offset:13920
	v_add_f32_e32 v145, v145, v8
	v_cvt_pk_bf16_f32 v8, v147, v2
	v_cvt_pk_bf16_f32 v80, v80, v0
	v_cvt_pk_bf16_f32 v82, v159, v82
	s_setprio 1
	s_waitcnt lgkmcnt(6)
	v_mfma_f32_32x32x16_bf16 v[48:63], v[68:71], v[8:11], v[48:63]
	v_mfma_f32_32x32x16_bf16 v[32:47], v[12:15], v[8:11], v[32:47]
	s_waitcnt lgkmcnt(5)
	v_mfma_f32_32x32x16_bf16 v[48:63], v[72:75], v[64:67], v[48:63]
	s_waitcnt lgkmcnt(4)
	v_mfma_f32_32x32x16_bf16 v[32:47], v[76:79], v[64:67], v[32:47]
	s_waitcnt lgkmcnt(3)
	v_mfma_f32_32x32x16_bf16 v[48:63], v[84:87], v[80:83], v[48:63]
	s_waitcnt lgkmcnt(2)
	v_mfma_f32_32x32x16_bf16 v[32:47], v[88:91], v[80:83], v[32:47]
	s_waitcnt lgkmcnt(1)
	v_mfma_f32_32x32x16_bf16 v[48:63], v[160:163], v[92:95], v[48:63]
	s_waitcnt lgkmcnt(0)
	v_mfma_f32_32x32x16_bf16 v[32:47], v[164:167], v[92:95], v[32:47]
	s_setprio 0
	s_cmp_ge_i32 s21, s17
	s_cbranch_scc0 .LBB0_785

; #define LAS __attribute__((address_space(3)))
; __device__ __forceinline__ void b_mask_init(f32x16& p0, f32x16& p1, unsigned long long mw, int hi, float ref) {
;     const int n0 = (int)~((unsigned)mw >> (8 * hi)), n1 = (int)~((unsigned)(mw >> 32) >> (8 * hi)); const int nr = __float_as_int(-ref);
; #pragma unroll
;     for (int r = 0; r < 16; ++r) { const int bit = 16 * (r >> 3) + (r & 7);
;         const int e0 = __builtin_amdgcn_sbfe(n0, bit, 1), e1 = __builtin_amdgcn_sbfe(n1, bit, 1);
;         p0[r] = __int_as_float((e0 & (int)0xFF800000) | (~e0 & nr)); p1[r] = __int_as_float((e1 & (int)0xFF800000) | (~e1 & nr)); }
; }
; __device__ __forceinline__ float exp_tile(f32x16& p0, f32x16& p1) {
;     float sacc = 0.f;
; #pragma unroll
;     for (int r = 0; r < 16; ++r) { p0[r] = __builtin_amdgcn_exp2f(p0[r]); p1[r] = __builtin_amdgcn_exp2f(p1[r]);
;     ...
;         p0[r] = __builtin_amdgcn_exp2f(__builtin_amdgcn_logf(p0[r])); p1[r] = __builtin_amdgcn_exp2f(__builtin_amdgcn_logf(p1[r]));
;     ...
;         sacc += p0[r] + p1[r]; }
;     return sacc;
; }
; template <bool FIXED> __device__ __forceinline__ void attnB_blk(const bf16* Q, const bf16* K, const bf16* Vt, bf16* O, const unsigned long long* MASK, float ref, LAS unsigned char* lds, int vcu, int G, int tid) {
;     ...
;             for (int k = 0; k < 2; ++k) {
;                 if (it + k < ntile) {
;                     LAS unsigned char* buf = pb + k * KVBUF_B;
;                     f32x16 p0, p1; b_mask_init(p0, p1, k ? mb : ma, hi, FIXED ? ref : 0.f);
;                     qk_lds<false>(p0, p1, buf, qr, r32, hi);
;                     if (FIXED) l += exp_tile(p0, p1); else softmax_step(p0, p1, m, l, o0, o1);
;                     pv_lds(o0, o1, buf, p0, p1, r32, hi);
;                 }
;             }
;             if (it + 2 < ntl) { LAS unsigned char* nb = lds + (((it >> 1) + 1) & 1) * PAIR_B; kv_write(sa, nb, tid); kv_write(sb, nb + KVBUF_B, tid);
.LBB0_785:
	v_lshrrev_b32_e32 v0, v134, v4
	v_bfe_i32 v17, v0, 23, 1
	v_bfe_i32 v18, v0, 22, 1
	v_lshrrev_b32_e32 v2, v134, v5
	v_bfi_b32 v79, v17, v16, v240
	v_bfe_i32 v19, v0, 21, 1
	v_bfi_b32 v78, v18, v16, v240
	v_bfe_i32 v20, v0, 20, 1
	v_bfi_b32 v77, v19, v16, v240
	v_bfe_i32 v21, v0, 19, 1
	v_bfi_b32 v76, v20, v16, v240
	v_bfe_i32 v22, v0, 18, 1
	v_bfi_b32 v75, v21, v16, v240
	v_bfe_i32 v23, v0, 17, 1
	v_bfi_b32 v74, v22, v16, v240
	v_bfe_i32 v24, v0, 16, 1
	v_bfi_b32 v73, v23, v16, v240
	v_bfe_i32 v17, v0, 7, 1
	v_bfi_b32 v72, v24, v16, v240
	v_bfe_i32 v18, v0, 6, 1
	v_bfi_b32 v71, v17, v16, v240
	v_bfe_i32 v19, v0, 5, 1
	v_bfi_b32 v70, v18, v16, v240
	v_bfe_i32 v20, v0, 4, 1
	v_bfi_b32 v69, v19, v16, v240
	v_bfe_i32 v21, v0, 3, 1
	v_bfi_b32 v68, v20, v16, v240
	v_bfe_i32 v22, v0, 2, 1
	v_bfi_b32 v67, v21, v16, v240
	v_bfe_i32 v23, v0, 1, 1
	v_bfe_i32 v24, v0, 0, 1
	v_bfi_b32 v66, v22, v16, v240
	v_bfi_b32 v65, v23, v16, v240
	v_bfe_i32 v17, v2, 23, 1
	v_bfi_b32 v64, v24, v16, v240
	v_bfe_i32 v18, v2, 22, 1
	v_bfi_b32 v95, v17, v16, v240
	v_bfe_i32 v19, v2, 21, 1
	v_bfi_b32 v94, v18, v16, v240
	v_bfe_i32 v20, v2, 20, 1
	v_bfi_b32 v93, v19, v16, v240
	v_bfe_i32 v21, v2, 19, 1
	v_bfi_b32 v92, v20, v16, v240
	v_bfe_i32 v22, v2, 18, 1
	v_bfi_b32 v91, v21, v16, v240
	v_bfe_i32 v23, v2, 17, 1
	v_bfi_b32 v90, v22, v16, v240
	v_bfe_i32 v24, v2, 16, 1
	v_bfi_b32 v89, v23, v16, v240
	v_bfe_i32 v17, v2, 7, 1
	v_bfi_b32 v88, v24, v16, v240
	v_bfe_i32 v18, v2, 6, 1
	v_bfi_b32 v87, v17, v16, v240
	v_bfe_i32 v19, v2, 5, 1
	v_bfi_b32 v86, v18, v16, v240
	v_bfe_i32 v20, v2, 4, 1
	v_bfi_b32 v85, v19, v16, v240
	v_bfe_i32 v21, v2, 3, 1
	v_bfi_b32 v84, v20, v16, v240
	v_bfe_i32 v22, v2, 2, 1
	v_bfi_b32 v83, v21, v16, v240
	v_bfe_i32 v23, v2, 1, 1
	v_bfi_b32 v82, v22, v16, v240
	v_bfe_i32 v24, v2, 0, 1
	ds_read_b128 v[2:5], v7 offset:23040
	ds_read_b128 v[8:11], v7 offset:18432
	ds_read_b128 v[12:15], v7 offset:18464
	ds_read_b128 v[160:163], v7 offset:23072
	ds_read_b128 v[164:167], v7 offset:18496
	ds_read_b128 v[168:171], v7 offset:23104
	ds_read_b128 v[172:175], v7 offset:18528
	ds_read_b128 v[176:179], v7 offset:23136
	v_bfi_b32 v81, v23, v16, v240
	v_bfi_b32 v80, v24, v16, v240
	s_setprio 1
	s_waitcnt lgkmcnt(6)
	v_mfma_f32_32x32x16_bf16 v[64:79], v[8:11], v[96:99], v[64:79]
	v_mfma_f32_32x32x16_bf16 v[80:95], v[2:5], v[96:99], v[80:95]
	s_waitcnt lgkmcnt(5)
	v_mfma_f32_32x32x16_bf16 v[64:79], v[12:15], v[100:103], v[64:79]
	s_waitcnt lgkmcnt(4)
	v_mfma_f32_32x32x16_bf16 v[80:95], v[160:163], v[100:103], v[80:95]
	s_waitcnt lgkmcnt(3)
	v_mfma_f32_32x32x16_bf16 v[64:79], v[164:167], v[108:111], v[64:79]
	s_waitcnt lgkmcnt(2)
	v_mfma_f32_32x32x16_bf16 v[80:95], v[168:171], v[108:111], v[80:95]
	s_waitcnt lgkmcnt(1)
	v_mfma_f32_32x32x16_bf16 v[64:79], v[172:175], v[112:115], v[64:79]
	s_waitcnt lgkmcnt(0)
	v_mfma_f32_32x32x16_bf16 v[80:95], v[176:179], v[112:115], v[80:95]
	s_setprio 0
	s_nop 8
	v_exp_f32_e32 v7, v64
	s_nop 0
	v_exp_f32_e32 v147, v80
	v_exp_f32_e32 v2, v65
	v_exp_f32_e32 v0, v81
	v_exp_f32_e32 v159, v82
	v_add_f32_e32 v3, v7, v147
	v_exp_f32_e32 v88, v88
	v_add_f32_e32 v4, v2, v0
	v_add_f32_e32 v5, v3, v1
	v_exp_f32_e32 v3, v66
	v_add_f32_e32 v81, v4, v5
	v_exp_f32_e32 v4, v67
	v_exp_f32_e32 v80, v83
	v_add_f32_e32 v5, v3, v159
	v_cvt_pk_bf16_f32 v2, v7, v2
	v_cvt_pk_bf16_f32 v3, v3, v4
	v_add_f32_e32 v8, v4, v80
	v_add_f32_e32 v9, v5, v81
	v_exp_f32_e32 v5, v68
	v_add_f32_e32 v83, v8, v9
	v_exp_f32_e32 v81, v84
	v_exp_f32_e32 v8, v69
	v_exp_f32_e32 v82, v85
	v_add_f32_e32 v9, v5, v81
	v_cvt_pk_bf16_f32 v4, v5, v8
	v_add_f32_e32 v10, v8, v82
	v_add_f32_e32 v11, v9, v83
	v_exp_f32_e32 v9, v70
	v_add_f32_e32 v85, v10, v11
	v_exp_f32_e32 v83, v86
	v_exp_f32_e32 v10, v71
	v_exp_f32_e32 v84, v87
	v_exp_f32_e32 v70, v72
	v_add_f32_e32 v11, v9, v83
	v_cvt_pk_bf16_f32 v5, v9, v10
	v_add_f32_e32 v12, v10, v84
	v_add_f32_e32 v13, v11, v85
	s_nop 0
	v_add_f32_e32 v161, v12, v13
	v_exp_f32_e32 v12, v73
	v_exp_f32_e32 v160, v89
	v_add_f32_e32 v13, v70, v88
	v_exp_f32_e32 v89, v90
	v_add_f32_e32 v14, v12, v160
	v_add_f32_e32 v15, v13, v161
	s_nop 0
	v_add_f32_e32 v163, v14, v15
	v_exp_f32_e32 v13, v74
	v_exp_f32_e32 v14, v75
	v_exp_f32_e32 v162, v91
	v_exp_f32_e32 v161, v92
	v_add_f32_e32 v15, v13, v89
	v_cvt_pk_bf16_f32 v12, v70, v12
	v_add_f32_e32 v64, v14, v162
	v_add_f32_e32 v65, v15, v163
	v_exp_f32_e32 v15, v76
	v_add_f32_e32 v91, v64, v65
	v_exp_f32_e32 v64, v77
	v_exp_f32_e32 v90, v93
	v_add_f32_e32 v65, v15, v161
	v_cvt_pk_bf16_f32 v13, v13, v14
	v_cvt_pk_bf16_f32 v14, v15, v64
	v_add_f32_e32 v66, v64, v90
	v_add_f32_e32 v67, v65, v91
	v_exp_f32_e32 v65, v78
	v_add_f32_e32 v93, v66, v67
	v_exp_f32_e32 v91, v94
	v_exp_f32_e32 v66, v79
	v_exp_f32_e32 v92, v95
	v_cvt_pk_bf16_f32 v77, v159, v80
	v_add_f32_e32 v67, v65, v91
	v_cvt_pk_bf16_f32 v15, v65, v66
	v_add_f32_e32 v68, v66, v92
	v_add_f32_e32 v69, v67, v93
	v_cvt_pk_bf16_f32 v78, v81, v82
	v_add_f32_e32 v11, v68, v69
	v_add_f32_e32 v145, v145, v11
	ds_read_b128 v[8:11], v6 offset:32256
	ds_read_b128 v[64:67], v6 offset:27648
	ds_read_b128 v[68:71], v6 offset:27680
	ds_read_b128 v[72:75], v6 offset:32288
	v_cvt_pk_bf16_f32 v79, v83, v84
	ds_read_b128 v[80:83], v6 offset:27712
	ds_read_b128 v[84:87], v6 offset:32320
	v_cvt_pk_bf16_f32 v88, v88, v160
	v_cvt_pk_bf16_f32 v89, v89, v162
	v_cvt_pk_bf16_f32 v90, v161, v90
	v_cvt_pk_bf16_f32 v91, v91, v92
	ds_read_b128 v[92:95], v6 offset:27744
	ds_read_b128 v[160:163], v6 offset:32352
	v_cvt_pk_bf16_f32 v76, v147, v0
	s_andn2_b64 vcc, exec, s[10:11]
	s_cbranch_vccnz .Lb2_pv_nowrite
	s_andn2_b32 s22, 1, s18
	s_mul_i32 s22, s22, 0x9000
	v_add_u32_e32 v0, s22, v133
	s_waitcnt vmcnt(3)
	ds_write_b128 v0, v[104:107]
	s_waitcnt vmcnt(2)
	ds_write_b128 v0, v[120:123] offset:9216
	s_waitcnt vmcnt(1)
	ds_write_b128 v0, v[124:127] offset:18432
	s_waitcnt vmcnt(0)
	ds_write_b128 v0, v[128:131] offset:27648
	s_setprio 1
	s_waitcnt lgkmcnt(10)
	v_mfma_f32_32x32x16_bf16 v[48:63], v[64:67], v[2:5], v[48:63]
	v_mfma_f32_32x32x16_bf16 v[32:47], v[8:11], v[2:5], v[32:47]
	s_waitcnt lgkmcnt(9)
	v_mfma_f32_32x32x16_bf16 v[48:63], v[68:71], v[12:15], v[48:63]
	s_waitcnt lgkmcnt(8)
	v_mfma_f32_32x32x16_bf16 v[32:47], v[72:75], v[12:15], v[32:47]
	s_waitcnt lgkmcnt(7)
	v_mfma_f32_32x32x16_bf16 v[48:63], v[80:83], v[76:79], v[48:63]
	s_waitcnt lgkmcnt(6)
	v_mfma_f32_32x32x16_bf16 v[32:47], v[84:87], v[76:79], v[32:47]
	s_waitcnt lgkmcnt(5)
	v_mfma_f32_32x32x16_bf16 v[48:63], v[92:95], v[88:91], v[48:63]
	s_waitcnt lgkmcnt(4)
	v_mfma_f32_32x32x16_bf16 v[32:47], v[160:163], v[88:91], v[32:47]
	s_setprio 0
	s_branch .LBB0_782
